# GEMM main loop: the 16 per-segment s_setprio flips removed
# speedup vs baseline: 1.0090x; 1.0090x over previous
.LBB0_744:
	s_add_i32 s44, s4, 2
	s_add_u32 s8, s6, 0x80
	s_addc_u32 s5, s7, 0
	s_add_i32 s45, 0, 0x10000
	v_add_u32_e32 v140, s45, v234
	ds_read_b128 v[128:131], v140
	ds_read_b128 v[132:135], v140 offset:1024
	ds_read_b128 v[136:139], v140 offset:2048
	ds_read_b128 v[140:143], v140 offset:3072
	s_cmp_eq_u32 s27, s4
	s_cselect_b32 s4, s90, s8
	s_cselect_b32 s5, s91, s5
	s_cselect_b32 s9, s93, s43
	s_cselect_b32 s8, s92, s42
	v_lshl_add_u64 v[214:215], s[6:7], 0, v[206:207]
	s_add_i32 m0, s74, 0xc000
	ds_read_b128 v[144:147], v235
	ds_read_b128 v[148:151], v235 offset:1024
	ds_read_b128 v[152:155], v235 offset:2048
	ds_read_b128 v[156:159], v235 offset:3072
	ds_read_b128 v[160:163], v235 offset:4096
	ds_read_b128 v[164:167], v235 offset:5120
	ds_read_b128 v[168:171], v235 offset:6144
	ds_read_b128 v[210:213], v235 offset:7168
	global_load_lds_dwordx4 v[214:215], off
	v_lshl_add_u64 v[214:215], s[6:7], 0, v[208:209]
	s_add_i32 m0, s74, 0xe000
	s_nop 0
	global_load_lds_dwordx4 v[214:215], off
	s_waitcnt lgkmcnt(8)
	s_barrier
	s_waitcnt lgkmcnt(0)
	s_waitcnt lgkmcnt(0)
	v_mfma_f32_16x16x32_bf16 v[108:111], v[128:131], v[144:147], v[108:111]
	v_mfma_f32_16x16x32_bf16 v[104:107], v[136:139], v[144:147], v[104:107]
	v_mfma_f32_16x16x32_bf16 v[92:95], v[128:131], v[152:155], v[92:95]
	v_mfma_f32_16x16x32_bf16 v[80:83], v[136:139], v[152:155], v[80:83]
	v_mfma_f32_16x16x32_bf16 v[68:71], v[128:131], v[160:163], v[68:71]
	v_mfma_f32_16x16x32_bf16 v[56:59], v[136:139], v[160:163], v[56:59]
	v_mfma_f32_16x16x32_bf16 v[44:47], v[128:131], v[168:171], v[44:47]
	v_mfma_f32_16x16x32_bf16 v[32:35], v[136:139], v[168:171], v[32:35]
	v_mfma_f32_16x16x32_bf16 v[108:111], v[132:135], v[148:151], v[108:111]
	v_mfma_f32_16x16x32_bf16 v[104:107], v[140:143], v[148:151], v[104:107]
	v_mfma_f32_16x16x32_bf16 v[92:95], v[132:135], v[156:159], v[92:95]
	v_mfma_f32_16x16x32_bf16 v[80:83], v[140:143], v[156:159], v[80:83]
	v_mfma_f32_16x16x32_bf16 v[68:71], v[132:135], v[164:167], v[68:71]
	v_mfma_f32_16x16x32_bf16 v[56:59], v[140:143], v[164:167], v[56:59]
	v_mfma_f32_16x16x32_bf16 v[44:47], v[132:135], v[210:213], v[44:47]
	v_mfma_f32_16x16x32_bf16 v[32:35], v[140:143], v[210:213], v[32:35]
	s_barrier
	s_add_i32 s45, s45, s97
	v_add_u32_e32 v172, s3, v234
	v_lshl_add_u64 v[244:245], s[8:9], 0, v[184:185]
	s_mov_b32 m0, s45
	ds_read_b128 v[214:217], v172
	ds_read_b128 v[218:221], v172 offset:1024
	ds_read_b128 v[236:239], v172 offset:2048
	ds_read_b128 v[240:243], v172 offset:3072
	global_load_lds_dwordx4 v[244:245], off
	v_lshl_add_u64 v[246:247], s[8:9], 0, v[188:189]
	s_add_i32 m0, s45, 0x2000
	s_nop 0
	global_load_lds_dwordx4 v[246:247], off
	s_barrier
	s_waitcnt lgkmcnt(0)
	s_waitcnt lgkmcnt(0)
	v_mfma_f32_16x16x32_bf16 v[124:127], v[214:217], v[144:147], v[124:127]
	v_mfma_f32_16x16x32_bf16 v[120:123], v[236:239], v[144:147], v[120:123]
	v_mfma_f32_16x16x32_bf16 v[116:119], v[214:217], v[152:155], v[116:119]
	v_mfma_f32_16x16x32_bf16 v[112:115], v[236:239], v[152:155], v[112:115]
	v_mfma_f32_16x16x32_bf16 v[100:103], v[214:217], v[160:163], v[100:103]
	v_mfma_f32_16x16x32_bf16 v[96:99], v[236:239], v[160:163], v[96:99]
	v_mfma_f32_16x16x32_bf16 v[76:79], v[214:217], v[168:171], v[76:79]
	v_mfma_f32_16x16x32_bf16 v[72:75], v[236:239], v[168:171], v[72:75]
	v_mfma_f32_16x16x32_bf16 v[124:127], v[218:221], v[148:151], v[124:127]
	v_mfma_f32_16x16x32_bf16 v[120:123], v[240:243], v[148:151], v[120:123]
	v_mfma_f32_16x16x32_bf16 v[116:119], v[218:221], v[156:159], v[116:119]
	v_mfma_f32_16x16x32_bf16 v[112:115], v[240:243], v[156:159], v[112:115]
	v_mfma_f32_16x16x32_bf16 v[100:103], v[218:221], v[164:167], v[100:103]
	v_mfma_f32_16x16x32_bf16 v[96:99], v[240:243], v[164:167], v[96:99]
	v_mfma_f32_16x16x32_bf16 v[76:79], v[218:221], v[210:213], v[76:79]
	v_mfma_f32_16x16x32_bf16 v[72:75], v[240:243], v[210:213], v[72:75]
	s_mov_b32 m0, s74
	v_lshl_add_u64 v[248:249], s[4:5], 0, v[182:183]
	s_barrier
	ds_read_b128 v[144:147], v235 offset:16384
	ds_read_b128 v[148:151], v235 offset:17408
	ds_read_b128 v[152:155], v235 offset:18432
	ds_read_b128 v[156:159], v235 offset:19456
	ds_read_b128 v[160:163], v235 offset:20480
	ds_read_b128 v[164:167], v235 offset:21504
	ds_read_b128 v[168:171], v235 offset:22528
	ds_read_b128 v[210:213], v235 offset:23552
	global_load_lds_dwordx4 v[248:249], off
	v_lshl_add_u64 v[250:251], s[4:5], 0, v[186:187]
	s_mov_b32 m0, s56
	s_nop 0
	global_load_lds_dwordx4 v[250:251], off
	s_barrier
	s_waitcnt lgkmcnt(0)
	s_waitcnt lgkmcnt(0)
	v_mfma_f32_16x16x32_bf16 v[52:55], v[128:131], v[144:147], v[52:55]
	v_mfma_f32_16x16x32_bf16 v[48:51], v[136:139], v[144:147], v[48:51]
	v_mfma_f32_16x16x32_bf16 v[28:31], v[128:131], v[152:155], v[28:31]
	v_mfma_f32_16x16x32_bf16 v[24:27], v[136:139], v[152:155], v[24:27]
	v_mfma_f32_16x16x32_bf16 v[12:15], v[128:131], v[160:163], v[12:15]
	v_mfma_f32_16x16x32_bf16 v[8:11], v[136:139], v[160:163], v[8:11]
	v_mfma_f32_16x16x32_bf16 v[4:7], v[128:131], v[168:171], v[4:7]
	v_mfma_f32_16x16x32_bf16 v[0:3], v[136:139], v[168:171], v[0:3]
	v_mfma_f32_16x16x32_bf16 v[52:55], v[132:135], v[148:151], v[52:55]
	v_mfma_f32_16x16x32_bf16 v[48:51], v[140:143], v[148:151], v[48:51]
	v_mfma_f32_16x16x32_bf16 v[28:31], v[132:135], v[156:159], v[28:31]
	v_mfma_f32_16x16x32_bf16 v[24:27], v[140:143], v[156:159], v[24:27]
	v_mfma_f32_16x16x32_bf16 v[12:15], v[132:135], v[164:167], v[12:15]
	v_mfma_f32_16x16x32_bf16 v[8:11], v[140:143], v[164:167], v[8:11]
	v_mfma_f32_16x16x32_bf16 v[4:7], v[132:135], v[210:213], v[4:7]
	v_mfma_f32_16x16x32_bf16 v[0:3], v[140:143], v[210:213], v[0:3]
	s_barrier
	s_add_u32 s8, s8, s78
	s_addc_u32 s9, s9, 0
	s_add_i32 s45, s3, s97
	v_lshl_add_u64 v[252:253], s[8:9], 0, v[184:185]
	s_mov_b32 m0, s45
	v_lshl_add_u64 v[230:231], s[8:9], 0, v[188:189]
	global_load_lds_dwordx4 v[252:253], off
	s_add_i32 m0, s45, 0x2000
	s_nop 0
	global_load_lds_dwordx4 v[230:231], off
	s_waitcnt vmcnt(6)
	s_barrier
	v_mfma_f32_16x16x32_bf16 v[88:91], v[214:217], v[144:147], v[88:91]
	v_mfma_f32_16x16x32_bf16 v[84:87], v[236:239], v[144:147], v[84:87]
	v_mfma_f32_16x16x32_bf16 v[64:67], v[214:217], v[152:155], v[64:67]
	v_mfma_f32_16x16x32_bf16 v[60:63], v[236:239], v[152:155], v[60:63]
	v_mfma_f32_16x16x32_bf16 v[40:43], v[214:217], v[160:163], v[40:43]
	v_mfma_f32_16x16x32_bf16 v[36:39], v[236:239], v[160:163], v[36:39]
	v_mfma_f32_16x16x32_bf16 v[20:23], v[214:217], v[168:171], v[20:23]
	v_mfma_f32_16x16x32_bf16 v[16:19], v[236:239], v[168:171], v[16:19]
	v_mfma_f32_16x16x32_bf16 v[88:91], v[218:221], v[148:151], v[88:91]
	v_mfma_f32_16x16x32_bf16 v[84:87], v[240:243], v[148:151], v[84:87]
	v_mfma_f32_16x16x32_bf16 v[64:67], v[218:221], v[156:159], v[64:67]
	v_mfma_f32_16x16x32_bf16 v[60:63], v[240:243], v[156:159], v[60:63]
	v_mfma_f32_16x16x32_bf16 v[40:43], v[218:221], v[164:167], v[40:43]
	v_mfma_f32_16x16x32_bf16 v[36:39], v[240:243], v[164:167], v[36:39]
	v_mfma_f32_16x16x32_bf16 v[20:23], v[218:221], v[210:213], v[20:23]
	v_mfma_f32_16x16x32_bf16 v[16:19], v[240:243], v[210:213], v[16:19]
	s_add_i32 s8, 0, 0x18000
	v_add_u32_e32 v140, s8, v234
	s_barrier
	ds_read_b128 v[128:131], v140
	ds_read_b128 v[132:135], v140 offset:1024
	ds_read_b128 v[136:139], v140 offset:2048
	ds_read_b128 v[140:143], v140 offset:3072
	s_add_u32 s4, s4, s60
	s_addc_u32 s5, s5, 0
	s_mov_b32 m0, s57
	v_lshl_add_u64 v[214:215], s[4:5], 0, v[182:183]
	ds_read_b128 v[144:147], v235 offset:32768
	ds_read_b128 v[148:151], v235 offset:33792
	ds_read_b128 v[152:155], v235 offset:34816
	ds_read_b128 v[156:159], v235 offset:35840
	ds_read_b128 v[160:163], v235 offset:36864
	ds_read_b128 v[164:167], v235 offset:37888
	ds_read_b128 v[168:171], v235 offset:38912
	ds_read_b128 v[210:213], v235 offset:39936
	global_load_lds_dwordx4 v[214:215], off
	v_lshl_add_u64 v[214:215], s[4:5], 0, v[186:187]
	s_mov_b32 m0, s68
	s_nop 0
	global_load_lds_dwordx4 v[214:215], off
	s_waitcnt lgkmcnt(8)
	s_barrier
	s_waitcnt lgkmcnt(0)
	s_waitcnt lgkmcnt(0)
	v_mfma_f32_16x16x32_bf16 v[108:111], v[128:131], v[144:147], v[108:111]
	v_mfma_f32_16x16x32_bf16 v[104:107], v[136:139], v[144:147], v[104:107]
	v_mfma_f32_16x16x32_bf16 v[92:95], v[128:131], v[152:155], v[92:95]
	v_mfma_f32_16x16x32_bf16 v[80:83], v[136:139], v[152:155], v[80:83]
	v_mfma_f32_16x16x32_bf16 v[68:71], v[128:131], v[160:163], v[68:71]
	v_mfma_f32_16x16x32_bf16 v[56:59], v[136:139], v[160:163], v[56:59]
	v_mfma_f32_16x16x32_bf16 v[44:47], v[128:131], v[168:171], v[44:47]
	v_mfma_f32_16x16x32_bf16 v[32:35], v[136:139], v[168:171], v[32:35]
	v_mfma_f32_16x16x32_bf16 v[108:111], v[132:135], v[148:151], v[108:111]
	v_mfma_f32_16x16x32_bf16 v[104:107], v[140:143], v[148:151], v[104:107]
	v_mfma_f32_16x16x32_bf16 v[92:95], v[132:135], v[156:159], v[92:95]
	v_mfma_f32_16x16x32_bf16 v[80:83], v[140:143], v[156:159], v[80:83]
	v_mfma_f32_16x16x32_bf16 v[68:71], v[132:135], v[164:167], v[68:71]
	v_mfma_f32_16x16x32_bf16 v[56:59], v[140:143], v[164:167], v[56:59]
	v_mfma_f32_16x16x32_bf16 v[44:47], v[132:135], v[210:213], v[44:47]
	v_mfma_f32_16x16x32_bf16 v[32:35], v[140:143], v[210:213], v[32:35]
	s_barrier
	s_add_i32 s4, 0, 0x1c000
	s_add_i32 s5, s8, s97
	v_add_u32_e32 v172, s4, v234
	v_lshl_add_u64 v[244:245], v[244:245], 0, s[54:55]
	s_mov_b32 m0, s5
	ds_read_b128 v[214:217], v172
	ds_read_b128 v[218:221], v172 offset:1024
	ds_read_b128 v[236:239], v172 offset:2048
	ds_read_b128 v[240:243], v172 offset:3072
	global_load_lds_dwordx4 v[244:245], off
	v_lshl_add_u64 v[244:245], v[246:247], 0, s[54:55]
	s_add_i32 m0, s5, 0x2000
	s_nop 0
	global_load_lds_dwordx4 v[244:245], off
	s_barrier
	s_waitcnt lgkmcnt(0)
	s_waitcnt lgkmcnt(0)
	v_mfma_f32_16x16x32_bf16 v[124:127], v[214:217], v[144:147], v[124:127]
	v_mfma_f32_16x16x32_bf16 v[120:123], v[236:239], v[144:147], v[120:123]
	v_mfma_f32_16x16x32_bf16 v[116:119], v[214:217], v[152:155], v[116:119]
	v_mfma_f32_16x16x32_bf16 v[112:115], v[236:239], v[152:155], v[112:115]
	v_mfma_f32_16x16x32_bf16 v[100:103], v[214:217], v[160:163], v[100:103]
	v_mfma_f32_16x16x32_bf16 v[96:99], v[236:239], v[160:163], v[96:99]
	v_mfma_f32_16x16x32_bf16 v[76:79], v[214:217], v[168:171], v[76:79]
	v_mfma_f32_16x16x32_bf16 v[72:75], v[236:239], v[168:171], v[72:75]
	v_mfma_f32_16x16x32_bf16 v[124:127], v[218:221], v[148:151], v[124:127]
	v_mfma_f32_16x16x32_bf16 v[120:123], v[240:243], v[148:151], v[120:123]
	v_mfma_f32_16x16x32_bf16 v[116:119], v[218:221], v[156:159], v[116:119]
	v_mfma_f32_16x16x32_bf16 v[112:115], v[240:243], v[156:159], v[112:115]
	v_mfma_f32_16x16x32_bf16 v[100:103], v[218:221], v[164:167], v[100:103]
	v_mfma_f32_16x16x32_bf16 v[96:99], v[240:243], v[164:167], v[96:99]
	v_mfma_f32_16x16x32_bf16 v[76:79], v[218:221], v[210:213], v[76:79]
	v_mfma_f32_16x16x32_bf16 v[72:75], v[240:243], v[210:213], v[72:75]
	s_mov_b32 m0, s69
	v_lshl_add_u64 v[244:245], v[248:249], 0, s[54:55]
	s_barrier
	ds_read_b128 v[144:147], v235 offset:49152
	ds_read_b128 v[148:151], v235 offset:50176
	ds_read_b128 v[152:155], v235 offset:51200
	ds_read_b128 v[156:159], v235 offset:52224
	ds_read_b128 v[160:163], v235 offset:53248
	ds_read_b128 v[164:167], v235 offset:54272
	ds_read_b128 v[168:171], v235 offset:55296
	ds_read_b128 v[210:213], v235 offset:56320
	global_load_lds_dwordx4 v[244:245], off
	v_lshl_add_u64 v[244:245], v[250:251], 0, s[54:55]
	s_mov_b32 m0, s26
	s_nop 0
	global_load_lds_dwordx4 v[244:245], off
	s_barrier
	s_waitcnt lgkmcnt(0)
	s_waitcnt lgkmcnt(0)
	v_mfma_f32_16x16x32_bf16 v[52:55], v[128:131], v[144:147], v[52:55]
	v_mfma_f32_16x16x32_bf16 v[48:51], v[136:139], v[144:147], v[48:51]
	v_mfma_f32_16x16x32_bf16 v[28:31], v[128:131], v[152:155], v[28:31]
	v_mfma_f32_16x16x32_bf16 v[24:27], v[136:139], v[152:155], v[24:27]
	v_mfma_f32_16x16x32_bf16 v[12:15], v[128:131], v[160:163], v[12:15]
	v_mfma_f32_16x16x32_bf16 v[8:11], v[136:139], v[160:163], v[8:11]
	v_mfma_f32_16x16x32_bf16 v[4:7], v[128:131], v[168:171], v[4:7]
	v_mfma_f32_16x16x32_bf16 v[0:3], v[136:139], v[168:171], v[0:3]
	v_mfma_f32_16x16x32_bf16 v[52:55], v[132:135], v[148:151], v[52:55]
	v_mfma_f32_16x16x32_bf16 v[48:51], v[140:143], v[148:151], v[48:51]
	v_mfma_f32_16x16x32_bf16 v[28:31], v[132:135], v[156:159], v[28:31]
	v_mfma_f32_16x16x32_bf16 v[24:27], v[140:143], v[156:159], v[24:27]
	v_mfma_f32_16x16x32_bf16 v[12:15], v[132:135], v[164:167], v[12:15]
	v_mfma_f32_16x16x32_bf16 v[8:11], v[140:143], v[164:167], v[8:11]
	v_mfma_f32_16x16x32_bf16 v[4:7], v[132:135], v[210:213], v[4:7]
	v_mfma_f32_16x16x32_bf16 v[0:3], v[140:143], v[210:213], v[0:3]
	s_barrier
	s_add_i32 s4, s4, s97
	v_lshl_add_u64 v[128:129], v[252:253], 0, s[54:55]
	s_mov_b32 m0, s4
	s_nop 0
	global_load_lds_dwordx4 v[128:129], off
	v_lshl_add_u64 v[128:129], v[230:231], 0, s[54:55]
	s_add_i32 m0, s4, 0x2000
	s_nop 0
	global_load_lds_dwordx4 v[128:129], off
	s_waitcnt vmcnt(6)
	s_barrier
	v_mfma_f32_16x16x32_bf16 v[88:91], v[214:217], v[144:147], v[88:91]
	v_mfma_f32_16x16x32_bf16 v[84:87], v[236:239], v[144:147], v[84:87]
	v_mfma_f32_16x16x32_bf16 v[64:67], v[214:217], v[152:155], v[64:67]
	v_mfma_f32_16x16x32_bf16 v[60:63], v[236:239], v[152:155], v[60:63]
	v_mfma_f32_16x16x32_bf16 v[40:43], v[214:217], v[160:163], v[40:43]
	v_mfma_f32_16x16x32_bf16 v[36:39], v[236:239], v[160:163], v[36:39]
	v_mfma_f32_16x16x32_bf16 v[20:23], v[214:217], v[168:171], v[20:23]
	v_mfma_f32_16x16x32_bf16 v[16:19], v[236:239], v[168:171], v[16:19]
	v_mfma_f32_16x16x32_bf16 v[88:91], v[218:221], v[148:151], v[88:91]
	v_mfma_f32_16x16x32_bf16 v[84:87], v[240:243], v[148:151], v[84:87]
	v_mfma_f32_16x16x32_bf16 v[64:67], v[218:221], v[156:159], v[64:67]
	v_mfma_f32_16x16x32_bf16 v[60:63], v[240:243], v[156:159], v[60:63]
	v_mfma_f32_16x16x32_bf16 v[40:43], v[218:221], v[164:167], v[40:43]
	v_mfma_f32_16x16x32_bf16 v[36:39], v[240:243], v[164:167], v[36:39]
	v_mfma_f32_16x16x32_bf16 v[20:23], v[218:221], v[210:213], v[20:23]
	v_mfma_f32_16x16x32_bf16 v[16:19], v[240:243], v[210:213], v[16:19]
	s_add_u32 s6, s6, 0x100
	s_addc_u32 s7, s7, 0
	s_add_u32 s42, s42, 0x100
	s_addc_u32 s43, s43, 0
	s_cmp_ge_u32 s44, s73
	s_mov_b32 s4, s44
	s_barrier
	s_cbranch_scc0 .LBB0_744
	s_lshl_b32 s52, s30, 8
	s_cmp_lt_i32 s96, 2
	s_mov_b64 s[4:5], -1
	s_cbranch_scc1 .LBB0_898
	s_cmp_gt_i32 s96, 2
	s_cbranch_scc0 .LBB0_895
	s_add_i32 s30, s52, s82
	v_or_b32_e32 v210, s30, v179
	s_and_b32 s4, s10, -4
	s_cmp_lg_u32 s4, 4
	s_movk_i32 s4, 0x2000
	s_movk_i32 s6, 0x1fff
	v_or_b32_e32 v212, 16, v210
	v_cmp_gt_i32_e32 vcc, s4, v210
	v_cmp_lt_i32_e64 s[42:43], s6, v210
	s_mov_b64 s[4:5], -1
	v_ashrrev_i32_e32 v211, 31, v210
	s_movk_i32 s53, 0x1fff
	v_cmp_lt_i32_e64 s[46:47], s6, v212
	s_cbranch_scc0 .LBB0_829
	v_lshlrev_b32_e32 v128, 6, v212
	s_movk_i32 s4, 0x2000
	v_and_b32_e32 v128, 0x3f7c0, v128
	v_cmp_gt_i32_e64 s[44:45], s4, v212
	v_lshlrev_b32_e32 v219, 6, v210
	v_and_b32_e32 v144, 0x3f3c0, v219
	v_cndmask_b32_e64 v128, v225, v128, s[44:45]
	v_lshlrev_b32_e32 v172, 2, v128
	v_cndmask_b32_e32 v144, v225, v144, vcc
	v_lshl_add_u64 v[132:133], v[196:197], 0, v[172:173]
	v_lshl_add_u64 v[140:141], v[198:199], 0, v[172:173]
	v_lshlrev_b32_e32 v172, 2, v144
	v_lshl_add_u64 v[144:145], v[198:199], 0, v[172:173]
	global_load_dwordx4 v[128:131], v[132:133], off offset:16
	global_load_dwordx4 v[136:139], v[132:133], off
	s_nop 0
	global_load_dwordx4 v[132:135], v[140:141], off offset:16
	s_nop 0
	global_load_dwordx4 v[140:143], v[140:141], off
	s_nop 0
	global_load_dwordx4 v[156:159], v[144:145], off offset:16
	global_load_dwordx4 v[152:155], v[144:145], off
	v_lshl_add_u64 v[144:145], v[196:197], 0, v[172:173]
	global_load_dwordx4 v[160:163], v[144:145], off offset:16
	global_load_dwordx4 v[164:167], v[144:145], off
	s_cmp_gt_i32 s10, 3
	s_cselect_b64 s[4:5], -1, 0
	s_lshl_b32 s6, s10, 1
	s_add_i32 s7, s6, -16
	s_cmp_lt_i32 s10, 4
	s_cselect_b32 s6, s6, s7
	v_readlane_b32 s7, v255, 50
	s_or_b32 s6, s6, s7
	s_lshl_b32 s94, s6, 7
	s_ashr_i32 s95, s94, 31
	s_lshl_b64 s[6:7], s[94:95], 1
	v_lshl_add_u64 v[214:215], v[200:201], 0, s[6:7]
	s_waitcnt vmcnt(0)
	v_pk_mul_f32 v[144:145], v[126:127], v[154:155]
	v_pk_mul_f32 v[148:149], v[124:125], v[152:153]
	v_pk_fma_f32 v[146:147], v[110:111], v[166:167], v[144:145] neg_lo:[0,0,1] neg_hi:[0,0,1]
	v_pk_fma_f32 v[144:145], v[108:109], v[164:165], v[148:149] neg_lo:[0,0,1] neg_hi:[0,0,1]
	v_pk_mul_f32 v[148:149], v[122:123], v[158:159]
	v_pk_mul_f32 v[168:169], v[120:121], v[156:157]
	v_pk_fma_f32 v[150:151], v[106:107], v[162:163], v[148:149] neg_lo:[0,0,1] neg_hi:[0,0,1]
	v_pk_fma_f32 v[148:149], v[104:105], v[160:161], v[168:169] neg_lo:[0,0,1] neg_hi:[0,0,1]
	v_pk_mul_f32 v[166:167], v[126:127], v[166:167]
	v_pk_mul_f32 v[164:165], v[124:125], v[164:165]
	v_pk_mul_f32 v[162:163], v[122:123], v[162:163]
	v_pk_mul_f32 v[160:161], v[120:121], v[160:161]
	v_pk_fma_f32 v[154:155], v[110:111], v[154:155], v[166:167]
	v_pk_fma_f32 v[152:153], v[108:109], v[152:153], v[164:165]
	v_pk_fma_f32 v[158:159], v[106:107], v[158:159], v[162:163]
	v_pk_fma_f32 v[156:157], v[104:105], v[156:157], v[160:161]
	v_cvt_pk_bf16_f32 v160, v144, v145
	v_cvt_pk_bf16_f32 v161, v146, v147
	v_cvt_pk_bf16_f32 v162, v148, v149
	v_cvt_pk_bf16_f32 v163, v150, v151
	v_cvt_pk_bf16_f32 v164, v152, v153
	v_cvt_pk_bf16_f32 v165, v154, v155
	v_cvt_pk_bf16_f32 v166, v156, v157
	v_cvt_pk_bf16_f32 v167, v158, v159
	s_mov_b64 s[8:9], -1
	s_and_b64 vcc, exec, s[4:5]
	s_cbranch_vccz .LBB0_750
	s_movk_i32 s8, 0x1800
	v_mad_i64_i32 v[168:169], s[8:9], v210, s8, v[214:215]
	global_store_dwordx4 v[168:169], v[160:163], off
	global_store_dwordx4 v[168:169], v[164:167], off offset:128
	s_mov_b64 s[8:9], 0
